# gMLP units rewritten by hand: per-unit loads prefetched one unit ahead with counted vmcnt, LayerNorm gains staged in LDS, LDS fragment reads pipelined against MFMAs
# speedup vs baseline: 1.0067x; 1.0067x over previous
.LBB0_567:
	s_or_b64 exec, exec, s[0:1]
	v_readlane_b32 s4, v242, 2
	v_readlane_b32 s5, v242, 3
	s_mov_b64 s[0:1], -1
	s_and_b64 vcc, exec, s[4:5]
	s_waitcnt lgkmcnt(0)
	s_barrier
	s_cbranch_vccz .LBB0_583
	s_mov_b64 s[6:7], s[46:47]
	v_mov_b32_e32 v83, v194
	v_readlane_b32 s4, v245, 58
	v_bfe_u32 v0, v83, 4, 2
	s_add_u32 s0, s6, 0x8200000
	v_lshlrev_b32_e32 v1, 2, v0
	v_lshl_add_u32 v82, v0, 4, 0
	v_lshlrev_b32_e32 v0, 3, v0
	v_readlane_b32 s5, v245, 59
	s_addc_u32 s1, s7, 0
	v_and_b32_e32 v84, 15, v83
	v_readfirstlane_b32 s12, v83
	s_andn2_b64 vcc, exec, s[4:5]
	v_lshlrev_b32_e32 v0, 1, v0
	v_lshlrev_b32_e32 v2, 1, v1
	s_cbranch_vccnz .LBB0_575
	v_and_b32_e32 v77, 0x7f, v83
	v_lshrrev_b32_e32 v89, 7, v83
	v_mul_u32_u24_e32 v1, 0x60, v77
	v_mul_u32_u24_e32 v85, 0x600, v77
	v_lshl_add_u32 v85, v89, 6, v85
	v_mul_u32_u24_e32 v86, 0x2200, v89
	v_lshl_add_u32 v86, v77, 1, v86
	v_and_b32_e32 v154, 15, v197
	v_lshrrev_b32_e32 v155, 4, v197
	v_mul_u32_u24_e32 v87, 0x110, v154
	v_lshl_add_u32 v87, v155, 4, v87
	v_lshlrev_b32_e32 v88, 7, v89
	v_add_u32_e32 v88, 0x9000, v88
	v_readfirstlane_b32 s19, v83
	s_nop 3
	s_lshr_b32 s19, s19, 6
	v_lshl_add_u32 v189, s19, 4, v154
	v_lshlrev_b32_e32 v90, 8, v189
	v_lshl_add_u32 v90, v155, 4, v90
	v_lshlrev_b32_e32 v91, 2, v189
	v_mul_u32_u24_e32 v92, 0x600, v189
	v_lshl_add_u32 v92, v155, 3, v92
	v_lshlrev_b32_e32 v93, 11, v189
	v_lshl_add_u32 v93, v155, 3, v93
	v_readlane_b32 s72, v246, 15
	v_readlane_b32 s73, v246, 16
	v_readlane_b32 s74, v246, 17
	v_readlane_b32 s75, v246, 18
	v_readlane_b32 s78, v246, 21
	v_readlane_b32 s79, v246, 22
	v_lshlrev_b32_e32 v77, 4, v83
	s_movk_i32 s28, 0xc0
	v_cmp_gt_u32_e32 vcc, s28, v83
	s_and_saveexec_b64 s[28:29], vcc
	s_cbranch_execz .Lgm_ng1
	global_load_dwordx4 v[200:203], v77, s[72:73]
	global_load_dwordx4 v[204:207], v77, s[74:75]
.Lgm_ng1:
	s_mov_b64 exec, s[28:29]
	s_mov_b32 s16, s2
	s_mul_hi_u32 s18, s16, 0xaaaaaaab
	s_lshr_b32 s18, s18, 2
	s_mul_i32 s17, s18, 6
	s_sub_u32 s17, s16, s17
	s_mul_i32 s28, s18, 0x3000
	s_add_u32 s4, s6, s28
	s_addc_u32 s5, s7, 0
	s_add_u32 s4, s4, 0x3600000
	s_addc_u32 s5, s5, 0
	global_load_dwordx4 v[4:7], v1, s[4:5]
	global_load_dwordx4 v[8:11], v1, s[4:5] offset:16
	global_load_dwordx4 v[12:15], v1, s[4:5] offset:32
	global_load_dwordx4 v[16:19], v1, s[4:5] offset:48
	global_load_dwordx4 v[20:23], v1, s[4:5] offset:64
	global_load_dwordx4 v[24:27], v1, s[4:5] offset:80
	s_mul_i32 s28, s18, 0x30000
	s_lshl_b32 s29, s17, 8
	s_add_u32 s28, s28, s29
	s_add_u32 s8, s6, s28
	s_addc_u32 s9, s7, 0
	s_add_u32 s14, s8, 0xd200000
	s_addc_u32 s15, s9, 0
	s_add_u32 s8, s8, 0x10200000
	s_addc_u32 s9, s9, 0
	global_load_dwordx4 v[28:31], v85, s[8:9]
	global_load_dwordx4 v[32:35], v85, s[8:9] offset:16
	global_load_dwordx4 v[36:39], v85, s[8:9] offset:32
	global_load_dwordx4 v[40:43], v85, s[8:9] offset:48
	s_lshl_b32 s28, s17, 15
	s_add_u32 s10, s6, s28
	s_addc_u32 s11, s7, 0
	s_add_u32 s10, s10, 0x3200000
	s_addc_u32 s11, s11, 0
	global_load_dwordx4 v[44:47], v90, s[10:11]
	global_load_dwordx4 v[48:51], v90, s[10:11] offset:64
	global_load_dwordx4 v[52:55], v90, s[10:11] offset:128
	global_load_dwordx4 v[56:59], v90, s[10:11] offset:192
	s_lshl_b32 s28, s17, 9
	s_add_u32 s12, s78, s28
	s_addc_u32 s13, s79, 0
	global_load_dword v76, v91, s[12:13]
	global_load_dwordx2 v[60:61], v92, s[14:15]
	global_load_dwordx2 v[62:63], v92, s[14:15] offset:32
	global_load_dwordx2 v[64:65], v92, s[14:15] offset:64
	global_load_dwordx2 v[66:67], v92, s[14:15] offset:96
	global_load_dwordx2 v[68:69], v92, s[14:15] offset:128
	global_load_dwordx2 v[70:71], v92, s[14:15] offset:160
	global_load_dwordx2 v[72:73], v92, s[14:15] offset:192
	global_load_dwordx2 v[74:75], v92, s[14:15] offset:224
	s_waitcnt vmcnt(23)
	s_movk_i32 s28, 0xc0
	v_cmp_gt_u32_e32 vcc, s28, v83
	s_and_saveexec_b64 s[28:29], vcc
	s_cbranch_execz .Lgm_ng2
	v_lshlrev_b32_e32 v77, 4, v83
	v_add_u32_e32 v77, 0x9000, v77
	ds_write_b128 v77, v[200:203]
	ds_write_b128 v77, v[204:207] offset:3072
.Lgm_ng2:
	s_mov_b64 exec, s[28:29]
	s_waitcnt lgkmcnt(0)
	s_barrier
	s_add_u32 s70, s16, s92
	s_min_u32 s71, s70, 0x5ff
	s_mul_hi_u32 s18, s71, 0xaaaaaaab
	s_lshr_b32 s18, s18, 2
	s_mul_i32 s17, s18, 6
	s_sub_u32 s17, s71, s17
	s_mul_i32 s28, s18, 0x3000
	s_add_u32 s4, s6, s28
	s_addc_u32 s5, s7, 0
	s_add_u32 s4, s4, 0x3600000
	s_addc_u32 s5, s5, 0
	global_load_dwordx4 v[98:101], v1, s[4:5]
	global_load_dwordx4 v[102:105], v1, s[4:5] offset:16
	global_load_dwordx4 v[106:109], v1, s[4:5] offset:32
	global_load_dwordx4 v[110:113], v1, s[4:5] offset:48
	global_load_dwordx4 v[114:117], v1, s[4:5] offset:64
	global_load_dwordx4 v[118:121], v1, s[4:5] offset:80
	s_mul_i32 s28, s18, 0x30000
	s_lshl_b32 s29, s17, 8
	s_add_u32 s28, s28, s29
	s_add_u32 s8, s6, s28
	s_addc_u32 s9, s7, 0
	s_add_u32 s14, s8, 0xd200000
	s_addc_u32 s15, s9, 0
	s_add_u32 s8, s8, 0x10200000
	s_addc_u32 s9, s9, 0
	global_load_dwordx4 v[122:125], v85, s[8:9]
	global_load_dwordx4 v[126:129], v85, s[8:9] offset:16
	global_load_dwordx4 v[130:133], v85, s[8:9] offset:32
	global_load_dwordx4 v[134:137], v85, s[8:9] offset:48
	s_lshl_b32 s28, s17, 15
	s_add_u32 s10, s6, s28
	s_addc_u32 s11, s7, 0
	s_add_u32 s10, s10, 0x3200000
	s_addc_u32 s11, s11, 0
	global_load_dwordx4 v[138:141], v90, s[10:11]
	global_load_dwordx4 v[142:145], v90, s[10:11] offset:64
	global_load_dwordx4 v[146:149], v90, s[10:11] offset:128
	global_load_dwordx4 v[150:153], v90, s[10:11] offset:192
	s_lshl_b32 s28, s17, 9
	s_add_u32 s12, s78, s28
	s_addc_u32 s13, s79, 0
	global_load_dword v188, v91, s[12:13]
	global_load_dwordx2 v[172:173], v92, s[14:15]
	global_load_dwordx2 v[174:175], v92, s[14:15] offset:32
	global_load_dwordx2 v[176:177], v92, s[14:15] offset:64
	global_load_dwordx2 v[178:179], v92, s[14:15] offset:96
	global_load_dwordx2 v[180:181], v92, s[14:15] offset:128
	global_load_dwordx2 v[182:183], v92, s[14:15] offset:160
	global_load_dwordx2 v[184:185], v92, s[14:15] offset:192
	global_load_dwordx2 v[186:187], v92, s[14:15] offset:224
	s_mul_hi_u32 s18, s16, 0xaaaaaaab
	s_lshr_b32 s18, s18, 2
	s_mul_i32 s17, s18, 6
	s_sub_u32 s17, s16, s17
	s_lshl_b32 s28, s17, 9
	v_add_u32_e32 v89, s28, v88
	s_mul_i32 s28, s18, 0x40000
	s_lshl_b32 s29, s17, 8
	s_add_u32 s28, s28, s29
	s_add_u32 s68, s0, s28
	s_addc_u32 s69, s1, 0
	s_waitcnt vmcnt(36)
	ds_read_b128 v[200:203], v89
	ds_read_b128 v[204:207], v89 offset:16
	ds_read_b128 v[208:211], v89 offset:3072
	ds_read_b128 v[212:215], v89 offset:3088
	v_add_f32_e32 v77, v4, v6
	v_add_f32_e32 v154, v5, v7
	v_add_f32_e32 v155, v8, v10
	v_add_f32_e32 v189, v9, v11
	v_add_f32_e32 v77, v77, v155
	v_add_f32_e32 v154, v154, v189
	v_add_f32_e32 v155, v12, v14
	v_add_f32_e32 v189, v13, v15
	v_add_f32_e32 v77, v77, v155
	v_add_f32_e32 v154, v154, v189
	v_add_f32_e32 v155, v16, v18
	v_add_f32_e32 v189, v17, v19
	v_add_f32_e32 v77, v77, v155
	v_add_f32_e32 v154, v154, v189
	v_add_f32_e32 v155, v20, v22
	v_add_f32_e32 v189, v21, v23
	v_add_f32_e32 v77, v77, v155
	v_add_f32_e32 v154, v154, v189
	v_add_f32_e32 v155, v24, v26
	v_add_f32_e32 v189, v25, v27
	v_add_f32_e32 v77, v77, v155
	v_add_f32_e32 v154, v154, v189
	v_mul_f32_e32 v155, 0x3aaaaaab, v77
	v_mul_f32_e32 v155, v155, v155
	s_mov_b32 s28, 0x3aaaaaab
	v_fma_f32 v154, v154, s28, -v155
	v_add_f32_e32 v154, 0x358637bd, v154
	v_rsq_f32_e32 v154, v154
	ds_read_b128 v[216:219], v89 offset:32
	ds_read_b128 v[220:223], v89 offset:48
	ds_read_b128 v[224:227], v89 offset:3104
	ds_read_b128 v[228:231], v89 offset:3120
	s_waitcnt lgkmcnt(4)
	v_lshlrev_b32_e32 v155, 16, v28
	v_and_b32_e32 v189, 0xffff0000, v28
	v_fmac_f32_e32 v155, 0xbaaaaaab, v77
	v_fmac_f32_e32 v189, 0xbaaaaaab, v77
	v_mul_f32_e32 v155, v155, v154
	v_mul_f32_e32 v189, v189, v154
	v_fma_f32 v155, v200, v155, v208
	v_fma_f32 v189, v201, v189, v209
	v_cvt_pk_bf16_f32 v28, v155, v189
	ds_write_b16 v86, v28
	ds_write_b16_d16_hi v86, v28 offset:272
	v_lshlrev_b32_e32 v155, 16, v29
	v_and_b32_e32 v189, 0xffff0000, v29
	v_fmac_f32_e32 v155, 0xbaaaaaab, v77
	v_fmac_f32_e32 v189, 0xbaaaaaab, v77
	v_mul_f32_e32 v155, v155, v154
	v_mul_f32_e32 v189, v189, v154
	v_fma_f32 v155, v202, v155, v210
	v_fma_f32 v189, v203, v189, v211
	v_cvt_pk_bf16_f32 v29, v155, v189
	ds_write_b16 v86, v29 offset:544
	ds_write_b16_d16_hi v86, v29 offset:816
	v_lshlrev_b32_e32 v155, 16, v30
	v_and_b32_e32 v189, 0xffff0000, v30
	v_fmac_f32_e32 v155, 0xbaaaaaab, v77
	v_fmac_f32_e32 v189, 0xbaaaaaab, v77
	v_mul_f32_e32 v155, v155, v154
	v_mul_f32_e32 v189, v189, v154
	v_fma_f32 v155, v204, v155, v212
	v_fma_f32 v189, v205, v189, v213
	v_cvt_pk_bf16_f32 v30, v155, v189
	ds_write_b16 v86, v30 offset:1088
	ds_write_b16_d16_hi v86, v30 offset:1360
	v_lshlrev_b32_e32 v155, 16, v31
	v_and_b32_e32 v189, 0xffff0000, v31
	v_fmac_f32_e32 v155, 0xbaaaaaab, v77
	v_fmac_f32_e32 v189, 0xbaaaaaab, v77
	v_mul_f32_e32 v155, v155, v154
	v_mul_f32_e32 v189, v189, v154
	v_fma_f32 v155, v206, v155, v214
	v_fma_f32 v189, v207, v189, v215
	v_cvt_pk_bf16_f32 v31, v155, v189
	ds_write_b16 v86, v31 offset:1632
	ds_write_b16_d16_hi v86, v31 offset:1904
	ds_read_b128 v[200:203], v89 offset:64
	ds_read_b128 v[204:207], v89 offset:80
	ds_read_b128 v[208:211], v89 offset:3136
	ds_read_b128 v[212:215], v89 offset:3152
	s_waitcnt lgkmcnt(4)
	v_lshlrev_b32_e32 v155, 16, v32
	v_and_b32_e32 v189, 0xffff0000, v32
	v_fmac_f32_e32 v155, 0xbaaaaaab, v77
	v_fmac_f32_e32 v189, 0xbaaaaaab, v77
	v_mul_f32_e32 v155, v155, v154
	v_mul_f32_e32 v189, v189, v154
	v_fma_f32 v155, v216, v155, v224
	v_fma_f32 v189, v217, v189, v225
	v_cvt_pk_bf16_f32 v32, v155, v189
	ds_write_b16 v86, v32 offset:2176
	ds_write_b16_d16_hi v86, v32 offset:2448
	v_lshlrev_b32_e32 v155, 16, v33
	v_and_b32_e32 v189, 0xffff0000, v33
	v_fmac_f32_e32 v155, 0xbaaaaaab, v77
	v_fmac_f32_e32 v189, 0xbaaaaaab, v77
	v_mul_f32_e32 v155, v155, v154
	v_mul_f32_e32 v189, v189, v154
	v_fma_f32 v155, v218, v155, v226
	v_fma_f32 v189, v219, v189, v227
	v_cvt_pk_bf16_f32 v33, v155, v189
	ds_write_b16 v86, v33 offset:2720
	ds_write_b16_d16_hi v86, v33 offset:2992
	v_lshlrev_b32_e32 v155, 16, v34
	v_and_b32_e32 v189, 0xffff0000, v34
	v_fmac_f32_e32 v155, 0xbaaaaaab, v77
	v_fmac_f32_e32 v189, 0xbaaaaaab, v77
	v_mul_f32_e32 v155, v155, v154
	v_mul_f32_e32 v189, v189, v154
	v_fma_f32 v155, v220, v155, v228
	v_fma_f32 v189, v221, v189, v229
	v_cvt_pk_bf16_f32 v34, v155, v189
	ds_write_b16 v86, v34 offset:3264
	ds_write_b16_d16_hi v86, v34 offset:3536
	v_lshlrev_b32_e32 v155, 16, v35
	v_and_b32_e32 v189, 0xffff0000, v35
	v_fmac_f32_e32 v155, 0xbaaaaaab, v77
	v_fmac_f32_e32 v189, 0xbaaaaaab, v77
	v_mul_f32_e32 v155, v155, v154
	v_mul_f32_e32 v189, v189, v154
	v_fma_f32 v155, v222, v155, v230
	v_fma_f32 v189, v223, v189, v231
	v_cvt_pk_bf16_f32 v35, v155, v189
	ds_write_b16 v86, v35 offset:3808
	ds_write_b16_d16_hi v86, v35 offset:4080
	ds_read_b128 v[216:219], v89 offset:96
	ds_read_b128 v[220:223], v89 offset:112
	ds_read_b128 v[224:227], v89 offset:3168
	ds_read_b128 v[228:231], v89 offset:3184
	s_waitcnt lgkmcnt(4)
	v_lshlrev_b32_e32 v155, 16, v36
	v_and_b32_e32 v189, 0xffff0000, v36
	v_fmac_f32_e32 v155, 0xbaaaaaab, v77
	v_fmac_f32_e32 v189, 0xbaaaaaab, v77
	v_mul_f32_e32 v155, v155, v154
	v_mul_f32_e32 v189, v189, v154
	v_fma_f32 v155, v200, v155, v208
	v_fma_f32 v189, v201, v189, v209
	v_cvt_pk_bf16_f32 v36, v155, v189
	ds_write_b16 v86, v36 offset:4352
	ds_write_b16_d16_hi v86, v36 offset:4624
	v_lshlrev_b32_e32 v155, 16, v37
	v_and_b32_e32 v189, 0xffff0000, v37
	v_fmac_f32_e32 v155, 0xbaaaaaab, v77
	v_fmac_f32_e32 v189, 0xbaaaaaab, v77
	v_mul_f32_e32 v155, v155, v154
	v_mul_f32_e32 v189, v189, v154
	v_fma_f32 v155, v202, v155, v210
	v_fma_f32 v189, v203, v189, v211
	v_cvt_pk_bf16_f32 v37, v155, v189
	ds_write_b16 v86, v37 offset:4896
	ds_write_b16_d16_hi v86, v37 offset:5168
	v_lshlrev_b32_e32 v155, 16, v38
	v_and_b32_e32 v189, 0xffff0000, v38
	v_fmac_f32_e32 v155, 0xbaaaaaab, v77
	v_fmac_f32_e32 v189, 0xbaaaaaab, v77
	v_mul_f32_e32 v155, v155, v154
	v_mul_f32_e32 v189, v189, v154
	v_fma_f32 v155, v204, v155, v212
	v_fma_f32 v189, v205, v189, v213
	v_cvt_pk_bf16_f32 v38, v155, v189
	ds_write_b16 v86, v38 offset:5440
	ds_write_b16_d16_hi v86, v38 offset:5712
	v_lshlrev_b32_e32 v155, 16, v39
	v_and_b32_e32 v189, 0xffff0000, v39
	v_fmac_f32_e32 v155, 0xbaaaaaab, v77
	v_fmac_f32_e32 v189, 0xbaaaaaab, v77
	v_mul_f32_e32 v155, v155, v154
	v_mul_f32_e32 v189, v189, v154
	v_fma_f32 v155, v206, v155, v214
	v_fma_f32 v189, v207, v189, v215
	v_cvt_pk_bf16_f32 v39, v155, v189
	ds_write_b16 v86, v39 offset:5984
	ds_write_b16_d16_hi v86, v39 offset:6256
	s_waitcnt lgkmcnt(0)
	v_lshlrev_b32_e32 v155, 16, v40
	v_and_b32_e32 v189, 0xffff0000, v40
	v_fmac_f32_e32 v155, 0xbaaaaaab, v77
	v_fmac_f32_e32 v189, 0xbaaaaaab, v77
	v_mul_f32_e32 v155, v155, v154
	v_mul_f32_e32 v189, v189, v154
	v_fma_f32 v155, v216, v155, v224
	v_fma_f32 v189, v217, v189, v225
	v_cvt_pk_bf16_f32 v40, v155, v189
	ds_write_b16 v86, v40 offset:6528
	ds_write_b16_d16_hi v86, v40 offset:6800
	v_lshlrev_b32_e32 v155, 16, v41
	v_and_b32_e32 v189, 0xffff0000, v41
	v_fmac_f32_e32 v155, 0xbaaaaaab, v77
	v_fmac_f32_e32 v189, 0xbaaaaaab, v77
	v_mul_f32_e32 v155, v155, v154
	v_mul_f32_e32 v189, v189, v154
	v_fma_f32 v155, v218, v155, v226
	v_fma_f32 v189, v219, v189, v227
	v_cvt_pk_bf16_f32 v41, v155, v189
	ds_write_b16 v86, v41 offset:7072
	ds_write_b16_d16_hi v86, v41 offset:7344
	v_lshlrev_b32_e32 v155, 16, v42
	v_and_b32_e32 v189, 0xffff0000, v42
	v_fmac_f32_e32 v155, 0xbaaaaaab, v77
	v_fmac_f32_e32 v189, 0xbaaaaaab, v77
	v_mul_f32_e32 v155, v155, v154
	v_mul_f32_e32 v189, v189, v154
	v_fma_f32 v155, v220, v155, v228
	v_fma_f32 v189, v221, v189, v229
	v_cvt_pk_bf16_f32 v42, v155, v189
	ds_write_b16 v86, v42 offset:7616
	ds_write_b16_d16_hi v86, v42 offset:7888
	v_lshlrev_b32_e32 v155, 16, v43
	v_and_b32_e32 v189, 0xffff0000, v43
	v_fmac_f32_e32 v155, 0xbaaaaaab, v77
	v_fmac_f32_e32 v189, 0xbaaaaaab, v77
	v_mul_f32_e32 v155, v155, v154
	v_mul_f32_e32 v189, v189, v154
	v_fma_f32 v155, v222, v155, v230
	v_fma_f32 v189, v223, v189, v231
	v_cvt_pk_bf16_f32 v43, v155, v189
	ds_write_b16 v86, v43 offset:8160
	ds_write_b16_d16_hi v86, v43 offset:8432
	s_waitcnt lgkmcnt(0)
	s_barrier
	s_waitcnt vmcnt(23)
	ds_read_b128 v[200:203], v87 offset:0
	ds_read_b128 v[204:207], v87 offset:64
	ds_read_b128 v[208:211], v87 offset:128
	ds_read_b128 v[212:215], v87 offset:192
	ds_read_b128 v[216:219], v87 offset:4352
	ds_read_b128 v[220:223], v87 offset:4416
	ds_read_b128 v[224:227], v87 offset:4480
	ds_read_b128 v[228:231], v87 offset:4544
	s_waitcnt lgkmcnt(4)
	v_mfma_f32_16x16x32_bf16 v[78:81], v[200:203], v[44:47], 0
	v_mfma_f32_16x16x32_bf16 v[78:81], v[204:207], v[48:51], v[78:81]
	v_mfma_f32_16x16x32_bf16 v[78:81], v[208:211], v[52:55], v[78:81]
	v_mfma_f32_16x16x32_bf16 v[78:81], v[212:215], v[56:59], v[78:81]
	ds_read_b128 v[200:203], v87 offset:8704
	ds_read_b128 v[204:207], v87 offset:8768
	ds_read_b128 v[208:211], v87 offset:8832
	ds_read_b128 v[212:215], v87 offset:8896
	s_waitcnt lgkmcnt(4)
	v_mfma_f32_16x16x32_bf16 v[94:97], v[216:219], v[44:47], 0
	v_mfma_f32_16x16x32_bf16 v[94:97], v[220:223], v[48:51], v[94:97]
	v_mfma_f32_16x16x32_bf16 v[94:97], v[224:227], v[52:55], v[94:97]
	v_mfma_f32_16x16x32_bf16 v[94:97], v[228:231], v[56:59], v[94:97]
	ds_read_b128 v[216:219], v87 offset:13056
	ds_read_b128 v[220:223], v87 offset:13120
	ds_read_b128 v[224:227], v87 offset:13184
	ds_read_b128 v[228:231], v87 offset:13248
	v_add_f32_e32 v78, v76, v78
	v_add_f32_e32 v79, v76, v79
	v_add_f32_e32 v80, v76, v80
	v_add_f32_e32 v81, v76, v81
	v_lshlrev_b32_e32 v155, 16, v60
	v_and_b32_e32 v189, 0xffff0000, v60
	v_mul_f32_e32 v78, v78, v155
	v_mul_f32_e32 v79, v79, v189
	v_lshlrev_b32_e32 v155, 16, v61
	v_and_b32_e32 v189, 0xffff0000, v61
	v_mul_f32_e32 v80, v80, v155
	v_mul_f32_e32 v81, v81, v189
	v_cvt_pk_bf16_f32 v60, v78, v79
	v_cvt_pk_bf16_f32 v61, v80, v81
	global_store_dwordx2 v93, v[60:61], s[68:69]
	s_waitcnt lgkmcnt(4)
	v_mfma_f32_16x16x32_bf16 v[78:81], v[200:203], v[44:47], 0
	v_mfma_f32_16x16x32_bf16 v[78:81], v[204:207], v[48:51], v[78:81]
	v_mfma_f32_16x16x32_bf16 v[78:81], v[208:211], v[52:55], v[78:81]
	v_mfma_f32_16x16x32_bf16 v[78:81], v[212:215], v[56:59], v[78:81]
	ds_read_b128 v[200:203], v87 offset:17408
	ds_read_b128 v[204:207], v87 offset:17472
	ds_read_b128 v[208:211], v87 offset:17536
	ds_read_b128 v[212:215], v87 offset:17600
	v_add_f32_e32 v94, v76, v94
	v_add_f32_e32 v95, v76, v95
	v_add_f32_e32 v96, v76, v96
	v_add_f32_e32 v97, v76, v97
	v_lshlrev_b32_e32 v155, 16, v62
	v_and_b32_e32 v189, 0xffff0000, v62
	v_mul_f32_e32 v94, v94, v155
	v_mul_f32_e32 v95, v95, v189
	v_lshlrev_b32_e32 v155, 16, v63
	v_and_b32_e32 v189, 0xffff0000, v63
	v_mul_f32_e32 v96, v96, v155
	v_mul_f32_e32 v97, v97, v189
	v_cvt_pk_bf16_f32 v62, v94, v95
	v_cvt_pk_bf16_f32 v63, v96, v97
	global_store_dwordx2 v93, v[62:63], s[68:69] offset:32
	s_waitcnt lgkmcnt(4)
	v_mfma_f32_16x16x32_bf16 v[94:97], v[216:219], v[44:47], 0
	v_mfma_f32_16x16x32_bf16 v[94:97], v[220:223], v[48:51], v[94:97]
	v_mfma_f32_16x16x32_bf16 v[94:97], v[224:227], v[52:55], v[94:97]
	v_mfma_f32_16x16x32_bf16 v[94:97], v[228:231], v[56:59], v[94:97]
	ds_read_b128 v[216:219], v87 offset:21760
	ds_read_b128 v[220:223], v87 offset:21824
	ds_read_b128 v[224:227], v87 offset:21888
	ds_read_b128 v[228:231], v87 offset:21952
	v_add_f32_e32 v78, v76, v78
	v_add_f32_e32 v79, v76, v79
	v_add_f32_e32 v80, v76, v80
	v_add_f32_e32 v81, v76, v81
	v_lshlrev_b32_e32 v155, 16, v64
	v_and_b32_e32 v189, 0xffff0000, v64
	v_mul_f32_e32 v78, v78, v155
	v_mul_f32_e32 v79, v79, v189
	v_lshlrev_b32_e32 v155, 16, v65
	v_and_b32_e32 v189, 0xffff0000, v65
	v_mul_f32_e32 v80, v80, v155
	v_mul_f32_e32 v81, v81, v189
	v_cvt_pk_bf16_f32 v64, v78, v79
	v_cvt_pk_bf16_f32 v65, v80, v81
	global_store_dwordx2 v93, v[64:65], s[68:69] offset:64
	s_waitcnt lgkmcnt(4)
	v_mfma_f32_16x16x32_bf16 v[78:81], v[200:203], v[44:47], 0
	v_mfma_f32_16x16x32_bf16 v[78:81], v[204:207], v[48:51], v[78:81]
	v_mfma_f32_16x16x32_bf16 v[78:81], v[208:211], v[52:55], v[78:81]
	v_mfma_f32_16x16x32_bf16 v[78:81], v[212:215], v[56:59], v[78:81]
	ds_read_b128 v[200:203], v87 offset:26112
	ds_read_b128 v[204:207], v87 offset:26176
	ds_read_b128 v[208:211], v87 offset:26240
	ds_read_b128 v[212:215], v87 offset:26304
	v_add_f32_e32 v94, v76, v94
	v_add_f32_e32 v95, v76, v95
	v_add_f32_e32 v96, v76, v96
	v_add_f32_e32 v97, v76, v97
	v_lshlrev_b32_e32 v155, 16, v66
	v_and_b32_e32 v189, 0xffff0000, v66
	v_mul_f32_e32 v94, v94, v155
	v_mul_f32_e32 v95, v95, v189
	v_lshlrev_b32_e32 v155, 16, v67
	v_and_b32_e32 v189, 0xffff0000, v67
	v_mul_f32_e32 v96, v96, v155
	v_mul_f32_e32 v97, v97, v189
	v_cvt_pk_bf16_f32 v66, v94, v95
	v_cvt_pk_bf16_f32 v67, v96, v97
	global_store_dwordx2 v93, v[66:67], s[68:69] offset:96
	s_waitcnt lgkmcnt(4)
	v_mfma_f32_16x16x32_bf16 v[94:97], v[216:219], v[44:47], 0
	v_mfma_f32_16x16x32_bf16 v[94:97], v[220:223], v[48:51], v[94:97]
	v_mfma_f32_16x16x32_bf16 v[94:97], v[224:227], v[52:55], v[94:97]
	v_mfma_f32_16x16x32_bf16 v[94:97], v[228:231], v[56:59], v[94:97]
	ds_read_b128 v[216:219], v87 offset:30464
	ds_read_b128 v[220:223], v87 offset:30528
	ds_read_b128 v[224:227], v87 offset:30592
	ds_read_b128 v[228:231], v87 offset:30656
	v_add_f32_e32 v78, v76, v78
	v_add_f32_e32 v79, v76, v79
	v_add_f32_e32 v80, v76, v80
	v_add_f32_e32 v81, v76, v81
	v_lshlrev_b32_e32 v155, 16, v68
	v_and_b32_e32 v189, 0xffff0000, v68
	v_mul_f32_e32 v78, v78, v155
	v_mul_f32_e32 v79, v79, v189
	v_lshlrev_b32_e32 v155, 16, v69
	v_and_b32_e32 v189, 0xffff0000, v69
	v_mul_f32_e32 v80, v80, v155
	v_mul_f32_e32 v81, v81, v189
	v_cvt_pk_bf16_f32 v68, v78, v79
	v_cvt_pk_bf16_f32 v69, v80, v81
	global_store_dwordx2 v93, v[68:69], s[68:69] offset:128
	s_waitcnt lgkmcnt(4)
	v_mfma_f32_16x16x32_bf16 v[78:81], v[200:203], v[44:47], 0
	v_mfma_f32_16x16x32_bf16 v[78:81], v[204:207], v[48:51], v[78:81]
	v_mfma_f32_16x16x32_bf16 v[78:81], v[208:211], v[52:55], v[78:81]
	v_mfma_f32_16x16x32_bf16 v[78:81], v[212:215], v[56:59], v[78:81]
	v_add_f32_e32 v94, v76, v94
	v_add_f32_e32 v95, v76, v95
	v_add_f32_e32 v96, v76, v96
	v_add_f32_e32 v97, v76, v97
	v_lshlrev_b32_e32 v155, 16, v70
	v_and_b32_e32 v189, 0xffff0000, v70
	v_mul_f32_e32 v94, v94, v155
	v_mul_f32_e32 v95, v95, v189
	v_lshlrev_b32_e32 v155, 16, v71
	v_and_b32_e32 v189, 0xffff0000, v71
	v_mul_f32_e32 v96, v96, v155
	v_mul_f32_e32 v97, v97, v189
	v_cvt_pk_bf16_f32 v70, v94, v95
	v_cvt_pk_bf16_f32 v71, v96, v97
	global_store_dwordx2 v93, v[70:71], s[68:69] offset:160
	s_waitcnt lgkmcnt(0)
	v_mfma_f32_16x16x32_bf16 v[94:97], v[216:219], v[44:47], 0
	v_mfma_f32_16x16x32_bf16 v[94:97], v[220:223], v[48:51], v[94:97]
	v_mfma_f32_16x16x32_bf16 v[94:97], v[224:227], v[52:55], v[94:97]
	v_mfma_f32_16x16x32_bf16 v[94:97], v[228:231], v[56:59], v[94:97]
	v_add_f32_e32 v78, v76, v78
	v_add_f32_e32 v79, v76, v79
	v_add_f32_e32 v80, v76, v80
	v_add_f32_e32 v81, v76, v81
	v_lshlrev_b32_e32 v155, 16, v72
	v_and_b32_e32 v189, 0xffff0000, v72
	v_mul_f32_e32 v78, v78, v155
	v_mul_f32_e32 v79, v79, v189
	v_lshlrev_b32_e32 v155, 16, v73
	v_and_b32_e32 v189, 0xffff0000, v73
	v_mul_f32_e32 v80, v80, v155
	v_mul_f32_e32 v81, v81, v189
	v_cvt_pk_bf16_f32 v72, v78, v79
	v_cvt_pk_bf16_f32 v73, v80, v81
	global_store_dwordx2 v93, v[72:73], s[68:69] offset:192
	s_nop 7
	v_add_f32_e32 v94, v76, v94
	v_add_f32_e32 v95, v76, v95
	v_add_f32_e32 v96, v76, v96
	v_add_f32_e32 v97, v76, v97
	v_lshlrev_b32_e32 v155, 16, v74
	v_and_b32_e32 v189, 0xffff0000, v74
	v_mul_f32_e32 v94, v94, v155
	v_mul_f32_e32 v95, v95, v189
	v_lshlrev_b32_e32 v155, 16, v75
	v_and_b32_e32 v189, 0xffff0000, v75
	v_mul_f32_e32 v96, v96, v155
	v_mul_f32_e32 v97, v97, v189
	v_cvt_pk_bf16_f32 v74, v94, v95
	v_cvt_pk_bf16_f32 v75, v96, v97
	global_store_dwordx2 v93, v[74:75], s[68:69] offset:224
	s_barrier
	s_mov_b32 s16, s70
	s_cmpk_lt_u32 s16, 0x600
	s_cbranch_scc0 .Lgm_done
.Lgm_loop:
	s_add_u32 s70, s16, s92
	s_min_u32 s71, s70, 0x5ff
	s_mul_hi_u32 s18, s71, 0xaaaaaaab
	s_lshr_b32 s18, s18, 2
	s_mul_i32 s17, s18, 6
	s_sub_u32 s17, s71, s17
	s_mul_i32 s28, s18, 0x3000
	s_add_u32 s4, s6, s28
	s_addc_u32 s5, s7, 0
	s_add_u32 s4, s4, 0x3600000
	s_addc_u32 s5, s5, 0
	global_load_dwordx4 v[4:7], v1, s[4:5]
	global_load_dwordx4 v[8:11], v1, s[4:5] offset:16
	global_load_dwordx4 v[12:15], v1, s[4:5] offset:32
	global_load_dwordx4 v[16:19], v1, s[4:5] offset:48
	global_load_dwordx4 v[20:23], v1, s[4:5] offset:64
	global_load_dwordx4 v[24:27], v1, s[4:5] offset:80
	s_mul_i32 s28, s18, 0x30000
	s_lshl_b32 s29, s17, 8
	s_add_u32 s28, s28, s29
	s_add_u32 s8, s6, s28
	s_addc_u32 s9, s7, 0
	s_add_u32 s14, s8, 0xd200000
	s_addc_u32 s15, s9, 0
	s_add_u32 s8, s8, 0x10200000
	s_addc_u32 s9, s9, 0
	global_load_dwordx4 v[28:31], v85, s[8:9]
	global_load_dwordx4 v[32:35], v85, s[8:9] offset:16
	global_load_dwordx4 v[36:39], v85, s[8:9] offset:32
	global_load_dwordx4 v[40:43], v85, s[8:9] offset:48
	s_lshl_b32 s28, s17, 15
	s_add_u32 s10, s6, s28
	s_addc_u32 s11, s7, 0
	s_add_u32 s10, s10, 0x3200000
	s_addc_u32 s11, s11, 0
	global_load_dwordx4 v[44:47], v90, s[10:11]
	global_load_dwordx4 v[48:51], v90, s[10:11] offset:64
	global_load_dwordx4 v[52:55], v90, s[10:11] offset:128
	global_load_dwordx4 v[56:59], v90, s[10:11] offset:192
	s_lshl_b32 s28, s17, 9
	s_add_u32 s12, s78, s28
	s_addc_u32 s13, s79, 0
	global_load_dword v76, v91, s[12:13]
	global_load_dwordx2 v[60:61], v92, s[14:15]
	global_load_dwordx2 v[62:63], v92, s[14:15] offset:32
	global_load_dwordx2 v[64:65], v92, s[14:15] offset:64
	global_load_dwordx2 v[66:67], v92, s[14:15] offset:96
	global_load_dwordx2 v[68:69], v92, s[14:15] offset:128
	global_load_dwordx2 v[70:71], v92, s[14:15] offset:160
	global_load_dwordx2 v[72:73], v92, s[14:15] offset:192
	global_load_dwordx2 v[74:75], v92, s[14:15] offset:224
	s_mul_hi_u32 s18, s16, 0xaaaaaaab
	s_lshr_b32 s18, s18, 2
	s_mul_i32 s17, s18, 6
	s_sub_u32 s17, s16, s17
	s_lshl_b32 s28, s17, 9
	v_add_u32_e32 v89, s28, v88
	s_mul_i32 s28, s18, 0x40000
	s_lshl_b32 s29, s17, 8
	s_add_u32 s28, s28, s29
	s_add_u32 s68, s0, s28
	s_addc_u32 s69, s1, 0
	s_waitcnt vmcnt(44)
	ds_read_b128 v[200:203], v89
	ds_read_b128 v[204:207], v89 offset:16
	ds_read_b128 v[208:211], v89 offset:3072
	ds_read_b128 v[212:215], v89 offset:3088
	v_add_f32_e32 v77, v98, v100
	v_add_f32_e32 v154, v99, v101
	v_add_f32_e32 v155, v102, v104
	v_add_f32_e32 v189, v103, v105
	v_add_f32_e32 v77, v77, v155
	v_add_f32_e32 v154, v154, v189
	v_add_f32_e32 v155, v106, v108
	v_add_f32_e32 v189, v107, v109
	v_add_f32_e32 v77, v77, v155
	v_add_f32_e32 v154, v154, v189
	v_add_f32_e32 v155, v110, v112
	v_add_f32_e32 v189, v111, v113
	v_add_f32_e32 v77, v77, v155
	v_add_f32_e32 v154, v154, v189
	v_add_f32_e32 v155, v114, v116
	v_add_f32_e32 v189, v115, v117
	v_add_f32_e32 v77, v77, v155
	v_add_f32_e32 v154, v154, v189
	v_add_f32_e32 v155, v118, v120
	v_add_f32_e32 v189, v119, v121
	v_add_f32_e32 v77, v77, v155
	v_add_f32_e32 v154, v154, v189
	v_mul_f32_e32 v155, 0x3aaaaaab, v77
	v_mul_f32_e32 v155, v155, v155
	s_mov_b32 s28, 0x3aaaaaab
	v_fma_f32 v154, v154, s28, -v155
	v_add_f32_e32 v154, 0x358637bd, v154
	v_rsq_f32_e32 v154, v154
	ds_read_b128 v[216:219], v89 offset:32
	ds_read_b128 v[220:223], v89 offset:48
	ds_read_b128 v[224:227], v89 offset:3104
	ds_read_b128 v[228:231], v89 offset:3120
	s_waitcnt lgkmcnt(4)
	v_lshlrev_b32_e32 v155, 16, v122
	v_and_b32_e32 v189, 0xffff0000, v122
	v_fmac_f32_e32 v155, 0xbaaaaaab, v77
	v_fmac_f32_e32 v189, 0xbaaaaaab, v77
	v_mul_f32_e32 v155, v155, v154
	v_mul_f32_e32 v189, v189, v154
	v_fma_f32 v155, v200, v155, v208
	v_fma_f32 v189, v201, v189, v209
	v_cvt_pk_bf16_f32 v122, v155, v189
	ds_write_b16 v86, v122
	ds_write_b16_d16_hi v86, v122 offset:272
	v_lshlrev_b32_e32 v155, 16, v123
	v_and_b32_e32 v189, 0xffff0000, v123
	v_fmac_f32_e32 v155, 0xbaaaaaab, v77
	v_fmac_f32_e32 v189, 0xbaaaaaab, v77
	v_mul_f32_e32 v155, v155, v154
	v_mul_f32_e32 v189, v189, v154
	v_fma_f32 v155, v202, v155, v210
	v_fma_f32 v189, v203, v189, v211
	v_cvt_pk_bf16_f32 v123, v155, v189
	ds_write_b16 v86, v123 offset:544
	ds_write_b16_d16_hi v86, v123 offset:816
	v_lshlrev_b32_e32 v155, 16, v124
	v_and_b32_e32 v189, 0xffff0000, v124
	v_fmac_f32_e32 v155, 0xbaaaaaab, v77
	v_fmac_f32_e32 v189, 0xbaaaaaab, v77
	v_mul_f32_e32 v155, v155, v154
	v_mul_f32_e32 v189, v189, v154
	v_fma_f32 v155, v204, v155, v212
	v_fma_f32 v189, v205, v189, v213
	v_cvt_pk_bf16_f32 v124, v155, v189
	ds_write_b16 v86, v124 offset:1088
	ds_write_b16_d16_hi v86, v124 offset:1360
	v_lshlrev_b32_e32 v155, 16, v125
	v_and_b32_e32 v189, 0xffff0000, v125
	v_fmac_f32_e32 v155, 0xbaaaaaab, v77
	v_fmac_f32_e32 v189, 0xbaaaaaab, v77
	v_mul_f32_e32 v155, v155, v154
	v_mul_f32_e32 v189, v189, v154
	v_fma_f32 v155, v206, v155, v214
	v_fma_f32 v189, v207, v189, v215
	v_cvt_pk_bf16_f32 v125, v155, v189
	ds_write_b16 v86, v125 offset:1632
	ds_write_b16_d16_hi v86, v125 offset:1904
	ds_read_b128 v[200:203], v89 offset:64
	ds_read_b128 v[204:207], v89 offset:80
	ds_read_b128 v[208:211], v89 offset:3136
	ds_read_b128 v[212:215], v89 offset:3152
	s_waitcnt lgkmcnt(4)
	v_lshlrev_b32_e32 v155, 16, v126
	v_and_b32_e32 v189, 0xffff0000, v126
	v_fmac_f32_e32 v155, 0xbaaaaaab, v77
	v_fmac_f32_e32 v189, 0xbaaaaaab, v77
	v_mul_f32_e32 v155, v155, v154
	v_mul_f32_e32 v189, v189, v154
	v_fma_f32 v155, v216, v155, v224
	v_fma_f32 v189, v217, v189, v225
	v_cvt_pk_bf16_f32 v126, v155, v189
	ds_write_b16 v86, v126 offset:2176
	ds_write_b16_d16_hi v86, v126 offset:2448
	v_lshlrev_b32_e32 v155, 16, v127
	v_and_b32_e32 v189, 0xffff0000, v127
	v_fmac_f32_e32 v155, 0xbaaaaaab, v77
	v_fmac_f32_e32 v189, 0xbaaaaaab, v77
	v_mul_f32_e32 v155, v155, v154
	v_mul_f32_e32 v189, v189, v154
	v_fma_f32 v155, v218, v155, v226
	v_fma_f32 v189, v219, v189, v227
	v_cvt_pk_bf16_f32 v127, v155, v189
	ds_write_b16 v86, v127 offset:2720
	ds_write_b16_d16_hi v86, v127 offset:2992
	v_lshlrev_b32_e32 v155, 16, v128
	v_and_b32_e32 v189, 0xffff0000, v128
	v_fmac_f32_e32 v155, 0xbaaaaaab, v77
	v_fmac_f32_e32 v189, 0xbaaaaaab, v77
	v_mul_f32_e32 v155, v155, v154
	v_mul_f32_e32 v189, v189, v154
	v_fma_f32 v155, v220, v155, v228
	v_fma_f32 v189, v221, v189, v229
	v_cvt_pk_bf16_f32 v128, v155, v189
	ds_write_b16 v86, v128 offset:3264
	ds_write_b16_d16_hi v86, v128 offset:3536
	v_lshlrev_b32_e32 v155, 16, v129
	v_and_b32_e32 v189, 0xffff0000, v129
	v_fmac_f32_e32 v155, 0xbaaaaaab, v77
	v_fmac_f32_e32 v189, 0xbaaaaaab, v77
	v_mul_f32_e32 v155, v155, v154
	v_mul_f32_e32 v189, v189, v154
	v_fma_f32 v155, v222, v155, v230
	v_fma_f32 v189, v223, v189, v231
	v_cvt_pk_bf16_f32 v129, v155, v189
	ds_write_b16 v86, v129 offset:3808
	ds_write_b16_d16_hi v86, v129 offset:4080
	ds_read_b128 v[216:219], v89 offset:96
	ds_read_b128 v[220:223], v89 offset:112
	ds_read_b128 v[224:227], v89 offset:3168
	ds_read_b128 v[228:231], v89 offset:3184
	s_waitcnt lgkmcnt(4)
	v_lshlrev_b32_e32 v155, 16, v130
	v_and_b32_e32 v189, 0xffff0000, v130
	v_fmac_f32_e32 v155, 0xbaaaaaab, v77
	v_fmac_f32_e32 v189, 0xbaaaaaab, v77
	v_mul_f32_e32 v155, v155, v154
	v_mul_f32_e32 v189, v189, v154
	v_fma_f32 v155, v200, v155, v208
	v_fma_f32 v189, v201, v189, v209
	v_cvt_pk_bf16_f32 v130, v155, v189
	ds_write_b16 v86, v130 offset:4352
	ds_write_b16_d16_hi v86, v130 offset:4624
	v_lshlrev_b32_e32 v155, 16, v131
	v_and_b32_e32 v189, 0xffff0000, v131
	v_fmac_f32_e32 v155, 0xbaaaaaab, v77
	v_fmac_f32_e32 v189, 0xbaaaaaab, v77
	v_mul_f32_e32 v155, v155, v154
	v_mul_f32_e32 v189, v189, v154
	v_fma_f32 v155, v202, v155, v210
	v_fma_f32 v189, v203, v189, v211
	v_cvt_pk_bf16_f32 v131, v155, v189
	ds_write_b16 v86, v131 offset:4896
	ds_write_b16_d16_hi v86, v131 offset:5168
	v_lshlrev_b32_e32 v155, 16, v132
	v_and_b32_e32 v189, 0xffff0000, v132
	v_fmac_f32_e32 v155, 0xbaaaaaab, v77
	v_fmac_f32_e32 v189, 0xbaaaaaab, v77
	v_mul_f32_e32 v155, v155, v154
	v_mul_f32_e32 v189, v189, v154
	v_fma_f32 v155, v204, v155, v212
	v_fma_f32 v189, v205, v189, v213
	v_cvt_pk_bf16_f32 v132, v155, v189
	ds_write_b16 v86, v132 offset:5440
	ds_write_b16_d16_hi v86, v132 offset:5712
	v_lshlrev_b32_e32 v155, 16, v133
	v_and_b32_e32 v189, 0xffff0000, v133
	v_fmac_f32_e32 v155, 0xbaaaaaab, v77
	v_fmac_f32_e32 v189, 0xbaaaaaab, v77
	v_mul_f32_e32 v155, v155, v154
	v_mul_f32_e32 v189, v189, v154
	v_fma_f32 v155, v206, v155, v214
	v_fma_f32 v189, v207, v189, v215
	v_cvt_pk_bf16_f32 v133, v155, v189
	ds_write_b16 v86, v133 offset:5984
	ds_write_b16_d16_hi v86, v133 offset:6256
	s_waitcnt lgkmcnt(0)
	v_lshlrev_b32_e32 v155, 16, v134
	v_and_b32_e32 v189, 0xffff0000, v134
	v_fmac_f32_e32 v155, 0xbaaaaaab, v77
	v_fmac_f32_e32 v189, 0xbaaaaaab, v77
	v_mul_f32_e32 v155, v155, v154
	v_mul_f32_e32 v189, v189, v154
	v_fma_f32 v155, v216, v155, v224
	v_fma_f32 v189, v217, v189, v225
	v_cvt_pk_bf16_f32 v134, v155, v189
	ds_write_b16 v86, v134 offset:6528
	ds_write_b16_d16_hi v86, v134 offset:6800
	v_lshlrev_b32_e32 v155, 16, v135
	v_and_b32_e32 v189, 0xffff0000, v135
	v_fmac_f32_e32 v155, 0xbaaaaaab, v77
	v_fmac_f32_e32 v189, 0xbaaaaaab, v77
	v_mul_f32_e32 v155, v155, v154
	v_mul_f32_e32 v189, v189, v154
	v_fma_f32 v155, v218, v155, v226
	v_fma_f32 v189, v219, v189, v227
	v_cvt_pk_bf16_f32 v135, v155, v189
	ds_write_b16 v86, v135 offset:7072
	ds_write_b16_d16_hi v86, v135 offset:7344
	v_lshlrev_b32_e32 v155, 16, v136
	v_and_b32_e32 v189, 0xffff0000, v136
	v_fmac_f32_e32 v155, 0xbaaaaaab, v77
	v_fmac_f32_e32 v189, 0xbaaaaaab, v77
	v_mul_f32_e32 v155, v155, v154
	v_mul_f32_e32 v189, v189, v154
	v_fma_f32 v155, v220, v155, v228
	v_fma_f32 v189, v221, v189, v229
	v_cvt_pk_bf16_f32 v136, v155, v189
	ds_write_b16 v86, v136 offset:7616
	ds_write_b16_d16_hi v86, v136 offset:7888
	v_lshlrev_b32_e32 v155, 16, v137
	v_and_b32_e32 v189, 0xffff0000, v137
	v_fmac_f32_e32 v155, 0xbaaaaaab, v77
	v_fmac_f32_e32 v189, 0xbaaaaaab, v77
	v_mul_f32_e32 v155, v155, v154
	v_mul_f32_e32 v189, v189, v154
	v_fma_f32 v155, v222, v155, v230
	v_fma_f32 v189, v223, v189, v231
	v_cvt_pk_bf16_f32 v137, v155, v189
	ds_write_b16 v86, v137 offset:8160
	ds_write_b16_d16_hi v86, v137 offset:8432
	s_waitcnt lgkmcnt(0)
	s_barrier
	s_waitcnt vmcnt(31)
	ds_read_b128 v[200:203], v87 offset:0
	ds_read_b128 v[204:207], v87 offset:64
	ds_read_b128 v[208:211], v87 offset:128
	ds_read_b128 v[212:215], v87 offset:192
	ds_read_b128 v[216:219], v87 offset:4352
	ds_read_b128 v[220:223], v87 offset:4416
	ds_read_b128 v[224:227], v87 offset:4480
	ds_read_b128 v[228:231], v87 offset:4544
	s_waitcnt lgkmcnt(4)
	v_mfma_f32_16x16x32_bf16 v[78:81], v[200:203], v[138:141], 0
	v_mfma_f32_16x16x32_bf16 v[78:81], v[204:207], v[142:145], v[78:81]
	v_mfma_f32_16x16x32_bf16 v[78:81], v[208:211], v[146:149], v[78:81]
	v_mfma_f32_16x16x32_bf16 v[78:81], v[212:215], v[150:153], v[78:81]
	ds_read_b128 v[200:203], v87 offset:8704
	ds_read_b128 v[204:207], v87 offset:8768
	ds_read_b128 v[208:211], v87 offset:8832
	ds_read_b128 v[212:215], v87 offset:8896
	s_waitcnt lgkmcnt(4)
	v_mfma_f32_16x16x32_bf16 v[94:97], v[216:219], v[138:141], 0
	v_mfma_f32_16x16x32_bf16 v[94:97], v[220:223], v[142:145], v[94:97]
	v_mfma_f32_16x16x32_bf16 v[94:97], v[224:227], v[146:149], v[94:97]
	v_mfma_f32_16x16x32_bf16 v[94:97], v[228:231], v[150:153], v[94:97]
	ds_read_b128 v[216:219], v87 offset:13056
	ds_read_b128 v[220:223], v87 offset:13120
	ds_read_b128 v[224:227], v87 offset:13184
	ds_read_b128 v[228:231], v87 offset:13248
	v_add_f32_e32 v78, v188, v78
	v_add_f32_e32 v79, v188, v79
	v_add_f32_e32 v80, v188, v80
	v_add_f32_e32 v81, v188, v81
	v_lshlrev_b32_e32 v155, 16, v172
	v_and_b32_e32 v189, 0xffff0000, v172
	v_mul_f32_e32 v78, v78, v155
	v_mul_f32_e32 v79, v79, v189
	v_lshlrev_b32_e32 v155, 16, v173
	v_and_b32_e32 v189, 0xffff0000, v173
	v_mul_f32_e32 v80, v80, v155
	v_mul_f32_e32 v81, v81, v189
	v_cvt_pk_bf16_f32 v172, v78, v79
	v_cvt_pk_bf16_f32 v173, v80, v81
	global_store_dwordx2 v93, v[172:173], s[68:69]
	s_waitcnt lgkmcnt(4)
	v_mfma_f32_16x16x32_bf16 v[78:81], v[200:203], v[138:141], 0
	v_mfma_f32_16x16x32_bf16 v[78:81], v[204:207], v[142:145], v[78:81]
	v_mfma_f32_16x16x32_bf16 v[78:81], v[208:211], v[146:149], v[78:81]
	v_mfma_f32_16x16x32_bf16 v[78:81], v[212:215], v[150:153], v[78:81]
	ds_read_b128 v[200:203], v87 offset:17408
	ds_read_b128 v[204:207], v87 offset:17472
	ds_read_b128 v[208:211], v87 offset:17536
	ds_read_b128 v[212:215], v87 offset:17600
	v_add_f32_e32 v94, v188, v94
	v_add_f32_e32 v95, v188, v95
	v_add_f32_e32 v96, v188, v96
	v_add_f32_e32 v97, v188, v97
	v_lshlrev_b32_e32 v155, 16, v174
	v_and_b32_e32 v189, 0xffff0000, v174
	v_mul_f32_e32 v94, v94, v155
	v_mul_f32_e32 v95, v95, v189
	v_lshlrev_b32_e32 v155, 16, v175
	v_and_b32_e32 v189, 0xffff0000, v175
	v_mul_f32_e32 v96, v96, v155
	v_mul_f32_e32 v97, v97, v189
	v_cvt_pk_bf16_f32 v174, v94, v95
	v_cvt_pk_bf16_f32 v175, v96, v97
	global_store_dwordx2 v93, v[174:175], s[68:69] offset:32
	s_waitcnt lgkmcnt(4)
	v_mfma_f32_16x16x32_bf16 v[94:97], v[216:219], v[138:141], 0
	v_mfma_f32_16x16x32_bf16 v[94:97], v[220:223], v[142:145], v[94:97]
	v_mfma_f32_16x16x32_bf16 v[94:97], v[224:227], v[146:149], v[94:97]
	v_mfma_f32_16x16x32_bf16 v[94:97], v[228:231], v[150:153], v[94:97]
	ds_read_b128 v[216:219], v87 offset:21760
	ds_read_b128 v[220:223], v87 offset:21824
	ds_read_b128 v[224:227], v87 offset:21888
	ds_read_b128 v[228:231], v87 offset:21952
	v_add_f32_e32 v78, v188, v78
	v_add_f32_e32 v79, v188, v79
	v_add_f32_e32 v80, v188, v80
	v_add_f32_e32 v81, v188, v81
	v_lshlrev_b32_e32 v155, 16, v176
	v_and_b32_e32 v189, 0xffff0000, v176
	v_mul_f32_e32 v78, v78, v155
	v_mul_f32_e32 v79, v79, v189
	v_lshlrev_b32_e32 v155, 16, v177
	v_and_b32_e32 v189, 0xffff0000, v177
	v_mul_f32_e32 v80, v80, v155
	v_mul_f32_e32 v81, v81, v189
	v_cvt_pk_bf16_f32 v176, v78, v79
	v_cvt_pk_bf16_f32 v177, v80, v81
	global_store_dwordx2 v93, v[176:177], s[68:69] offset:64
	s_waitcnt lgkmcnt(4)
	v_mfma_f32_16x16x32_bf16 v[78:81], v[200:203], v[138:141], 0
	v_mfma_f32_16x16x32_bf16 v[78:81], v[204:207], v[142:145], v[78:81]
	v_mfma_f32_16x16x32_bf16 v[78:81], v[208:211], v[146:149], v[78:81]
	v_mfma_f32_16x16x32_bf16 v[78:81], v[212:215], v[150:153], v[78:81]
	ds_read_b128 v[200:203], v87 offset:26112
	ds_read_b128 v[204:207], v87 offset:26176
	ds_read_b128 v[208:211], v87 offset:26240
	ds_read_b128 v[212:215], v87 offset:26304
	v_add_f32_e32 v94, v188, v94
	v_add_f32_e32 v95, v188, v95
	v_add_f32_e32 v96, v188, v96
	v_add_f32_e32 v97, v188, v97
	v_lshlrev_b32_e32 v155, 16, v178
	v_and_b32_e32 v189, 0xffff0000, v178
	v_mul_f32_e32 v94, v94, v155
	v_mul_f32_e32 v95, v95, v189
	v_lshlrev_b32_e32 v155, 16, v179
	v_and_b32_e32 v189, 0xffff0000, v179
	v_mul_f32_e32 v96, v96, v155
	v_mul_f32_e32 v97, v97, v189
	v_cvt_pk_bf16_f32 v178, v94, v95
	v_cvt_pk_bf16_f32 v179, v96, v97
	global_store_dwordx2 v93, v[178:179], s[68:69] offset:96
	s_waitcnt lgkmcnt(4)
	v_mfma_f32_16x16x32_bf16 v[94:97], v[216:219], v[138:141], 0
	v_mfma_f32_16x16x32_bf16 v[94:97], v[220:223], v[142:145], v[94:97]
	v_mfma_f32_16x16x32_bf16 v[94:97], v[224:227], v[146:149], v[94:97]
	v_mfma_f32_16x16x32_bf16 v[94:97], v[228:231], v[150:153], v[94:97]
	ds_read_b128 v[216:219], v87 offset:30464
	ds_read_b128 v[220:223], v87 offset:30528
	ds_read_b128 v[224:227], v87 offset:30592
	ds_read_b128 v[228:231], v87 offset:30656
	v_add_f32_e32 v78, v188, v78
	v_add_f32_e32 v79, v188, v79
	v_add_f32_e32 v80, v188, v80
	v_add_f32_e32 v81, v188, v81
	v_lshlrev_b32_e32 v155, 16, v180
	v_and_b32_e32 v189, 0xffff0000, v180
	v_mul_f32_e32 v78, v78, v155
	v_mul_f32_e32 v79, v79, v189
	v_lshlrev_b32_e32 v155, 16, v181
	v_and_b32_e32 v189, 0xffff0000, v181
	v_mul_f32_e32 v80, v80, v155
	v_mul_f32_e32 v81, v81, v189
	v_cvt_pk_bf16_f32 v180, v78, v79
	v_cvt_pk_bf16_f32 v181, v80, v81
	global_store_dwordx2 v93, v[180:181], s[68:69] offset:128
	s_waitcnt lgkmcnt(4)
	v_mfma_f32_16x16x32_bf16 v[78:81], v[200:203], v[138:141], 0
	v_mfma_f32_16x16x32_bf16 v[78:81], v[204:207], v[142:145], v[78:81]
	v_mfma_f32_16x16x32_bf16 v[78:81], v[208:211], v[146:149], v[78:81]
	v_mfma_f32_16x16x32_bf16 v[78:81], v[212:215], v[150:153], v[78:81]
	v_add_f32_e32 v94, v188, v94
	v_add_f32_e32 v95, v188, v95
	v_add_f32_e32 v96, v188, v96
	v_add_f32_e32 v97, v188, v97
	v_lshlrev_b32_e32 v155, 16, v182
	v_and_b32_e32 v189, 0xffff0000, v182
	v_mul_f32_e32 v94, v94, v155
	v_mul_f32_e32 v95, v95, v189
	v_lshlrev_b32_e32 v155, 16, v183
	v_and_b32_e32 v189, 0xffff0000, v183
	v_mul_f32_e32 v96, v96, v155
	v_mul_f32_e32 v97, v97, v189
	v_cvt_pk_bf16_f32 v182, v94, v95
	v_cvt_pk_bf16_f32 v183, v96, v97
	global_store_dwordx2 v93, v[182:183], s[68:69] offset:160
	s_waitcnt lgkmcnt(0)
	v_mfma_f32_16x16x32_bf16 v[94:97], v[216:219], v[138:141], 0
	v_mfma_f32_16x16x32_bf16 v[94:97], v[220:223], v[142:145], v[94:97]
	v_mfma_f32_16x16x32_bf16 v[94:97], v[224:227], v[146:149], v[94:97]
	v_mfma_f32_16x16x32_bf16 v[94:97], v[228:231], v[150:153], v[94:97]
	v_add_f32_e32 v78, v188, v78
	v_add_f32_e32 v79, v188, v79
	v_add_f32_e32 v80, v188, v80
	v_add_f32_e32 v81, v188, v81
	v_lshlrev_b32_e32 v155, 16, v184
	v_and_b32_e32 v189, 0xffff0000, v184
	v_mul_f32_e32 v78, v78, v155
	v_mul_f32_e32 v79, v79, v189
	v_lshlrev_b32_e32 v155, 16, v185
	v_and_b32_e32 v189, 0xffff0000, v185
	v_mul_f32_e32 v80, v80, v155
	v_mul_f32_e32 v81, v81, v189
	v_cvt_pk_bf16_f32 v184, v78, v79
	v_cvt_pk_bf16_f32 v185, v80, v81
	global_store_dwordx2 v93, v[184:185], s[68:69] offset:192
	s_nop 7
	v_add_f32_e32 v94, v188, v94
	v_add_f32_e32 v95, v188, v95
	v_add_f32_e32 v96, v188, v96
	v_add_f32_e32 v97, v188, v97
	v_lshlrev_b32_e32 v155, 16, v186
	v_and_b32_e32 v189, 0xffff0000, v186
	v_mul_f32_e32 v94, v94, v155
	v_mul_f32_e32 v95, v95, v189
	v_lshlrev_b32_e32 v155, 16, v187
	v_and_b32_e32 v189, 0xffff0000, v187
	v_mul_f32_e32 v96, v96, v155
	v_mul_f32_e32 v97, v97, v189
	v_cvt_pk_bf16_f32 v186, v94, v95
	v_cvt_pk_bf16_f32 v187, v96, v97
	global_store_dwordx2 v93, v[186:187], s[68:69] offset:224
	s_barrier
	s_mov_b32 s16, s70
	s_cmpk_lt_u32 s16, 0x600
	s_cbranch_scc0 .Lgm_done
	s_add_u32 s70, s16, s92
	s_min_u32 s71, s70, 0x5ff
	s_mul_hi_u32 s18, s71, 0xaaaaaaab
	s_lshr_b32 s18, s18, 2
	s_mul_i32 s17, s18, 6
	s_sub_u32 s17, s71, s17
	s_mul_i32 s28, s18, 0x3000
	s_add_u32 s4, s6, s28
	s_addc_u32 s5, s7, 0
	s_add_u32 s4, s4, 0x3600000
	s_addc_u32 s5, s5, 0
	global_load_dwordx4 v[98:101], v1, s[4:5]
	global_load_dwordx4 v[102:105], v1, s[4:5] offset:16
	global_load_dwordx4 v[106:109], v1, s[4:5] offset:32
	global_load_dwordx4 v[110:113], v1, s[4:5] offset:48
	global_load_dwordx4 v[114:117], v1, s[4:5] offset:64
	global_load_dwordx4 v[118:121], v1, s[4:5] offset:80
	s_mul_i32 s28, s18, 0x30000
	s_lshl_b32 s29, s17, 8
	s_add_u32 s28, s28, s29
	s_add_u32 s8, s6, s28
	s_addc_u32 s9, s7, 0
	s_add_u32 s14, s8, 0xd200000
	s_addc_u32 s15, s9, 0
	s_add_u32 s8, s8, 0x10200000
	s_addc_u32 s9, s9, 0
	global_load_dwordx4 v[122:125], v85, s[8:9]
	global_load_dwordx4 v[126:129], v85, s[8:9] offset:16
	global_load_dwordx4 v[130:133], v85, s[8:9] offset:32
	global_load_dwordx4 v[134:137], v85, s[8:9] offset:48
	s_lshl_b32 s28, s17, 15
	s_add_u32 s10, s6, s28
	s_addc_u32 s11, s7, 0
	s_add_u32 s10, s10, 0x3200000
	s_addc_u32 s11, s11, 0
	global_load_dwordx4 v[138:141], v90, s[10:11]
	global_load_dwordx4 v[142:145], v90, s[10:11] offset:64
	global_load_dwordx4 v[146:149], v90, s[10:11] offset:128
	global_load_dwordx4 v[150:153], v90, s[10:11] offset:192
	s_lshl_b32 s28, s17, 9
	s_add_u32 s12, s78, s28
	s_addc_u32 s13, s79, 0
	global_load_dword v188, v91, s[12:13]
	global_load_dwordx2 v[172:173], v92, s[14:15]
	global_load_dwordx2 v[174:175], v92, s[14:15] offset:32
	global_load_dwordx2 v[176:177], v92, s[14:15] offset:64
	global_load_dwordx2 v[178:179], v92, s[14:15] offset:96
	global_load_dwordx2 v[180:181], v92, s[14:15] offset:128
	global_load_dwordx2 v[182:183], v92, s[14:15] offset:160
	global_load_dwordx2 v[184:185], v92, s[14:15] offset:192
	global_load_dwordx2 v[186:187], v92, s[14:15] offset:224
	s_mul_hi_u32 s18, s16, 0xaaaaaaab
	s_lshr_b32 s18, s18, 2
	s_mul_i32 s17, s18, 6
	s_sub_u32 s17, s16, s17
	s_lshl_b32 s28, s17, 9
	v_add_u32_e32 v89, s28, v88
	s_mul_i32 s28, s18, 0x40000
	s_lshl_b32 s29, s17, 8
	s_add_u32 s28, s28, s29
	s_add_u32 s68, s0, s28
	s_addc_u32 s69, s1, 0
	s_waitcnt vmcnt(44)
	ds_read_b128 v[200:203], v89
	ds_read_b128 v[204:207], v89 offset:16
	ds_read_b128 v[208:211], v89 offset:3072
	ds_read_b128 v[212:215], v89 offset:3088
	v_add_f32_e32 v77, v4, v6
	v_add_f32_e32 v154, v5, v7
	v_add_f32_e32 v155, v8, v10
	v_add_f32_e32 v189, v9, v11
	v_add_f32_e32 v77, v77, v155
	v_add_f32_e32 v154, v154, v189
	v_add_f32_e32 v155, v12, v14
	v_add_f32_e32 v189, v13, v15
	v_add_f32_e32 v77, v77, v155
	v_add_f32_e32 v154, v154, v189
	v_add_f32_e32 v155, v16, v18
	v_add_f32_e32 v189, v17, v19
	v_add_f32_e32 v77, v77, v155
	v_add_f32_e32 v154, v154, v189
	v_add_f32_e32 v155, v20, v22
	v_add_f32_e32 v189, v21, v23
	v_add_f32_e32 v77, v77, v155
	v_add_f32_e32 v154, v154, v189
	v_add_f32_e32 v155, v24, v26
	v_add_f32_e32 v189, v25, v27
	v_add_f32_e32 v77, v77, v155
	v_add_f32_e32 v154, v154, v189
	v_mul_f32_e32 v155, 0x3aaaaaab, v77
	v_mul_f32_e32 v155, v155, v155
	s_mov_b32 s28, 0x3aaaaaab
	v_fma_f32 v154, v154, s28, -v155
	v_add_f32_e32 v154, 0x358637bd, v154
	v_rsq_f32_e32 v154, v154
	ds_read_b128 v[216:219], v89 offset:32
	ds_read_b128 v[220:223], v89 offset:48
	ds_read_b128 v[224:227], v89 offset:3104
	ds_read_b128 v[228:231], v89 offset:3120
	s_waitcnt lgkmcnt(4)
	v_lshlrev_b32_e32 v155, 16, v28
	v_and_b32_e32 v189, 0xffff0000, v28
	v_fmac_f32_e32 v155, 0xbaaaaaab, v77
	v_fmac_f32_e32 v189, 0xbaaaaaab, v77
	v_mul_f32_e32 v155, v155, v154
	v_mul_f32_e32 v189, v189, v154
	v_fma_f32 v155, v200, v155, v208
	v_fma_f32 v189, v201, v189, v209
	v_cvt_pk_bf16_f32 v28, v155, v189
	ds_write_b16 v86, v28
	ds_write_b16_d16_hi v86, v28 offset:272
	v_lshlrev_b32_e32 v155, 16, v29
	v_and_b32_e32 v189, 0xffff0000, v29
	v_fmac_f32_e32 v155, 0xbaaaaaab, v77
	v_fmac_f32_e32 v189, 0xbaaaaaab, v77
	v_mul_f32_e32 v155, v155, v154
	v_mul_f32_e32 v189, v189, v154
	v_fma_f32 v155, v202, v155, v210
	v_fma_f32 v189, v203, v189, v211
	v_cvt_pk_bf16_f32 v29, v155, v189
	ds_write_b16 v86, v29 offset:544
	ds_write_b16_d16_hi v86, v29 offset:816
	v_lshlrev_b32_e32 v155, 16, v30
	v_and_b32_e32 v189, 0xffff0000, v30
	v_fmac_f32_e32 v155, 0xbaaaaaab, v77
	v_fmac_f32_e32 v189, 0xbaaaaaab, v77
	v_mul_f32_e32 v155, v155, v154
	v_mul_f32_e32 v189, v189, v154
	v_fma_f32 v155, v204, v155, v212
	v_fma_f32 v189, v205, v189, v213
	v_cvt_pk_bf16_f32 v30, v155, v189
	ds_write_b16 v86, v30 offset:1088
	ds_write_b16_d16_hi v86, v30 offset:1360
	v_lshlrev_b32_e32 v155, 16, v31
	v_and_b32_e32 v189, 0xffff0000, v31
	v_fmac_f32_e32 v155, 0xbaaaaaab, v77
	v_fmac_f32_e32 v189, 0xbaaaaaab, v77
	v_mul_f32_e32 v155, v155, v154
	v_mul_f32_e32 v189, v189, v154
	v_fma_f32 v155, v206, v155, v214
	v_fma_f32 v189, v207, v189, v215
	v_cvt_pk_bf16_f32 v31, v155, v189
	ds_write_b16 v86, v31 offset:1632
	ds_write_b16_d16_hi v86, v31 offset:1904
	ds_read_b128 v[200:203], v89 offset:64
	ds_read_b128 v[204:207], v89 offset:80
	ds_read_b128 v[208:211], v89 offset:3136
	ds_read_b128 v[212:215], v89 offset:3152
	s_waitcnt lgkmcnt(4)
	v_lshlrev_b32_e32 v155, 16, v32
	v_and_b32_e32 v189, 0xffff0000, v32
	v_fmac_f32_e32 v155, 0xbaaaaaab, v77
	v_fmac_f32_e32 v189, 0xbaaaaaab, v77
	v_mul_f32_e32 v155, v155, v154
	v_mul_f32_e32 v189, v189, v154
	v_fma_f32 v155, v216, v155, v224
	v_fma_f32 v189, v217, v189, v225
	v_cvt_pk_bf16_f32 v32, v155, v189
	ds_write_b16 v86, v32 offset:2176
	ds_write_b16_d16_hi v86, v32 offset:2448
	v_lshlrev_b32_e32 v155, 16, v33
	v_and_b32_e32 v189, 0xffff0000, v33
	v_fmac_f32_e32 v155, 0xbaaaaaab, v77
	v_fmac_f32_e32 v189, 0xbaaaaaab, v77
	v_mul_f32_e32 v155, v155, v154
	v_mul_f32_e32 v189, v189, v154
	v_fma_f32 v155, v218, v155, v226
	v_fma_f32 v189, v219, v189, v227
	v_cvt_pk_bf16_f32 v33, v155, v189
	ds_write_b16 v86, v33 offset:2720
	ds_write_b16_d16_hi v86, v33 offset:2992
	v_lshlrev_b32_e32 v155, 16, v34
	v_and_b32_e32 v189, 0xffff0000, v34
	v_fmac_f32_e32 v155, 0xbaaaaaab, v77
	v_fmac_f32_e32 v189, 0xbaaaaaab, v77
	v_mul_f32_e32 v155, v155, v154
	v_mul_f32_e32 v189, v189, v154
	v_fma_f32 v155, v220, v155, v228
	v_fma_f32 v189, v221, v189, v229
	v_cvt_pk_bf16_f32 v34, v155, v189
	ds_write_b16 v86, v34 offset:3264
	ds_write_b16_d16_hi v86, v34 offset:3536
	v_lshlrev_b32_e32 v155, 16, v35
	v_and_b32_e32 v189, 0xffff0000, v35
	v_fmac_f32_e32 v155, 0xbaaaaaab, v77
	v_fmac_f32_e32 v189, 0xbaaaaaab, v77
	v_mul_f32_e32 v155, v155, v154
	v_mul_f32_e32 v189, v189, v154
	v_fma_f32 v155, v222, v155, v230
	v_fma_f32 v189, v223, v189, v231
	v_cvt_pk_bf16_f32 v35, v155, v189
	ds_write_b16 v86, v35 offset:3808
	ds_write_b16_d16_hi v86, v35 offset:4080
	ds_read_b128 v[216:219], v89 offset:96
	ds_read_b128 v[220:223], v89 offset:112
	ds_read_b128 v[224:227], v89 offset:3168
	ds_read_b128 v[228:231], v89 offset:3184
	s_waitcnt lgkmcnt(4)
	v_lshlrev_b32_e32 v155, 16, v36
	v_and_b32_e32 v189, 0xffff0000, v36
	v_fmac_f32_e32 v155, 0xbaaaaaab, v77
	v_fmac_f32_e32 v189, 0xbaaaaaab, v77
	v_mul_f32_e32 v155, v155, v154
	v_mul_f32_e32 v189, v189, v154
	v_fma_f32 v155, v200, v155, v208
	v_fma_f32 v189, v201, v189, v209
	v_cvt_pk_bf16_f32 v36, v155, v189
	ds_write_b16 v86, v36 offset:4352
	ds_write_b16_d16_hi v86, v36 offset:4624
	v_lshlrev_b32_e32 v155, 16, v37
	v_and_b32_e32 v189, 0xffff0000, v37
	v_fmac_f32_e32 v155, 0xbaaaaaab, v77
	v_fmac_f32_e32 v189, 0xbaaaaaab, v77
	v_mul_f32_e32 v155, v155, v154
	v_mul_f32_e32 v189, v189, v154
	v_fma_f32 v155, v202, v155, v210
	v_fma_f32 v189, v203, v189, v211
	v_cvt_pk_bf16_f32 v37, v155, v189
	ds_write_b16 v86, v37 offset:4896
	ds_write_b16_d16_hi v86, v37 offset:5168
	v_lshlrev_b32_e32 v155, 16, v38
	v_and_b32_e32 v189, 0xffff0000, v38
	v_fmac_f32_e32 v155, 0xbaaaaaab, v77
	v_fmac_f32_e32 v189, 0xbaaaaaab, v77
	v_mul_f32_e32 v155, v155, v154
	v_mul_f32_e32 v189, v189, v154
	v_fma_f32 v155, v204, v155, v212
	v_fma_f32 v189, v205, v189, v213
	v_cvt_pk_bf16_f32 v38, v155, v189
	ds_write_b16 v86, v38 offset:5440
	ds_write_b16_d16_hi v86, v38 offset:5712
	v_lshlrev_b32_e32 v155, 16, v39
	v_and_b32_e32 v189, 0xffff0000, v39
	v_fmac_f32_e32 v155, 0xbaaaaaab, v77
	v_fmac_f32_e32 v189, 0xbaaaaaab, v77
	v_mul_f32_e32 v155, v155, v154
	v_mul_f32_e32 v189, v189, v154
	v_fma_f32 v155, v206, v155, v214
	v_fma_f32 v189, v207, v189, v215
	v_cvt_pk_bf16_f32 v39, v155, v189
	ds_write_b16 v86, v39 offset:5984
	ds_write_b16_d16_hi v86, v39 offset:6256
	s_waitcnt lgkmcnt(0)
	v_lshlrev_b32_e32 v155, 16, v40
	v_and_b32_e32 v189, 0xffff0000, v40
	v_fmac_f32_e32 v155, 0xbaaaaaab, v77
	v_fmac_f32_e32 v189, 0xbaaaaaab, v77
	v_mul_f32_e32 v155, v155, v154
	v_mul_f32_e32 v189, v189, v154
	v_fma_f32 v155, v216, v155, v224
	v_fma_f32 v189, v217, v189, v225
	v_cvt_pk_bf16_f32 v40, v155, v189
	ds_write_b16 v86, v40 offset:6528
	ds_write_b16_d16_hi v86, v40 offset:6800
	v_lshlrev_b32_e32 v155, 16, v41
	v_and_b32_e32 v189, 0xffff0000, v41
	v_fmac_f32_e32 v155, 0xbaaaaaab, v77
	v_fmac_f32_e32 v189, 0xbaaaaaab, v77
	v_mul_f32_e32 v155, v155, v154
	v_mul_f32_e32 v189, v189, v154
	v_fma_f32 v155, v218, v155, v226
	v_fma_f32 v189, v219, v189, v227
	v_cvt_pk_bf16_f32 v41, v155, v189
	ds_write_b16 v86, v41 offset:7072
	ds_write_b16_d16_hi v86, v41 offset:7344
	v_lshlrev_b32_e32 v155, 16, v42
	v_and_b32_e32 v189, 0xffff0000, v42
	v_fmac_f32_e32 v155, 0xbaaaaaab, v77
	v_fmac_f32_e32 v189, 0xbaaaaaab, v77
	v_mul_f32_e32 v155, v155, v154
	v_mul_f32_e32 v189, v189, v154
	v_fma_f32 v155, v220, v155, v228
	v_fma_f32 v189, v221, v189, v229
	v_cvt_pk_bf16_f32 v42, v155, v189
	ds_write_b16 v86, v42 offset:7616
	ds_write_b16_d16_hi v86, v42 offset:7888
	v_lshlrev_b32_e32 v155, 16, v43
	v_and_b32_e32 v189, 0xffff0000, v43
	v_fmac_f32_e32 v155, 0xbaaaaaab, v77
	v_fmac_f32_e32 v189, 0xbaaaaaab, v77
	v_mul_f32_e32 v155, v155, v154
	v_mul_f32_e32 v189, v189, v154
	v_fma_f32 v155, v222, v155, v230
	v_fma_f32 v189, v223, v189, v231
	v_cvt_pk_bf16_f32 v43, v155, v189
	ds_write_b16 v86, v43 offset:8160
	ds_write_b16_d16_hi v86, v43 offset:8432
	s_waitcnt lgkmcnt(0)
	s_barrier
	s_waitcnt vmcnt(31)
	ds_read_b128 v[200:203], v87 offset:0
	ds_read_b128 v[204:207], v87 offset:64
	ds_read_b128 v[208:211], v87 offset:128
	ds_read_b128 v[212:215], v87 offset:192
	ds_read_b128 v[216:219], v87 offset:4352
	ds_read_b128 v[220:223], v87 offset:4416
	ds_read_b128 v[224:227], v87 offset:4480
	ds_read_b128 v[228:231], v87 offset:4544
	s_waitcnt lgkmcnt(4)
	v_mfma_f32_16x16x32_bf16 v[78:81], v[200:203], v[44:47], 0
	v_mfma_f32_16x16x32_bf16 v[78:81], v[204:207], v[48:51], v[78:81]
	v_mfma_f32_16x16x32_bf16 v[78:81], v[208:211], v[52:55], v[78:81]
	v_mfma_f32_16x16x32_bf16 v[78:81], v[212:215], v[56:59], v[78:81]
	ds_read_b128 v[200:203], v87 offset:8704
	ds_read_b128 v[204:207], v87 offset:8768
	ds_read_b128 v[208:211], v87 offset:8832
	ds_read_b128 v[212:215], v87 offset:8896
	s_waitcnt lgkmcnt(4)
	v_mfma_f32_16x16x32_bf16 v[94:97], v[216:219], v[44:47], 0
	v_mfma_f32_16x16x32_bf16 v[94:97], v[220:223], v[48:51], v[94:97]
	v_mfma_f32_16x16x32_bf16 v[94:97], v[224:227], v[52:55], v[94:97]
	v_mfma_f32_16x16x32_bf16 v[94:97], v[228:231], v[56:59], v[94:97]
	ds_read_b128 v[216:219], v87 offset:13056
	ds_read_b128 v[220:223], v87 offset:13120
	ds_read_b128 v[224:227], v87 offset:13184
	ds_read_b128 v[228:231], v87 offset:13248
	v_add_f32_e32 v78, v76, v78
	v_add_f32_e32 v79, v76, v79
	v_add_f32_e32 v80, v76, v80
	v_add_f32_e32 v81, v76, v81
	v_lshlrev_b32_e32 v155, 16, v60
	v_and_b32_e32 v189, 0xffff0000, v60
	v_mul_f32_e32 v78, v78, v155
	v_mul_f32_e32 v79, v79, v189
	v_lshlrev_b32_e32 v155, 16, v61
	v_and_b32_e32 v189, 0xffff0000, v61
	v_mul_f32_e32 v80, v80, v155
	v_mul_f32_e32 v81, v81, v189
	v_cvt_pk_bf16_f32 v60, v78, v79
	v_cvt_pk_bf16_f32 v61, v80, v81
	global_store_dwordx2 v93, v[60:61], s[68:69]
	s_waitcnt lgkmcnt(4)
	v_mfma_f32_16x16x32_bf16 v[78:81], v[200:203], v[44:47], 0
	v_mfma_f32_16x16x32_bf16 v[78:81], v[204:207], v[48:51], v[78:81]
	v_mfma_f32_16x16x32_bf16 v[78:81], v[208:211], v[52:55], v[78:81]
	v_mfma_f32_16x16x32_bf16 v[78:81], v[212:215], v[56:59], v[78:81]
	ds_read_b128 v[200:203], v87 offset:17408
	ds_read_b128 v[204:207], v87 offset:17472
	ds_read_b128 v[208:211], v87 offset:17536
	ds_read_b128 v[212:215], v87 offset:17600
	v_add_f32_e32 v94, v76, v94
	v_add_f32_e32 v95, v76, v95
	v_add_f32_e32 v96, v76, v96
	v_add_f32_e32 v97, v76, v97
	v_lshlrev_b32_e32 v155, 16, v62
	v_and_b32_e32 v189, 0xffff0000, v62
	v_mul_f32_e32 v94, v94, v155
	v_mul_f32_e32 v95, v95, v189
	v_lshlrev_b32_e32 v155, 16, v63
	v_and_b32_e32 v189, 0xffff0000, v63
	v_mul_f32_e32 v96, v96, v155
	v_mul_f32_e32 v97, v97, v189
	v_cvt_pk_bf16_f32 v62, v94, v95
	v_cvt_pk_bf16_f32 v63, v96, v97
	global_store_dwordx2 v93, v[62:63], s[68:69] offset:32
	s_waitcnt lgkmcnt(4)
	v_mfma_f32_16x16x32_bf16 v[94:97], v[216:219], v[44:47], 0
	v_mfma_f32_16x16x32_bf16 v[94:97], v[220:223], v[48:51], v[94:97]
	v_mfma_f32_16x16x32_bf16 v[94:97], v[224:227], v[52:55], v[94:97]
	v_mfma_f32_16x16x32_bf16 v[94:97], v[228:231], v[56:59], v[94:97]
	ds_read_b128 v[216:219], v87 offset:21760
	ds_read_b128 v[220:223], v87 offset:21824
	ds_read_b128 v[224:227], v87 offset:21888
	ds_read_b128 v[228:231], v87 offset:21952
	v_add_f32_e32 v78, v76, v78
	v_add_f32_e32 v79, v76, v79
	v_add_f32_e32 v80, v76, v80
	v_add_f32_e32 v81, v76, v81
	v_lshlrev_b32_e32 v155, 16, v64
	v_and_b32_e32 v189, 0xffff0000, v64
	v_mul_f32_e32 v78, v78, v155
	v_mul_f32_e32 v79, v79, v189
	v_lshlrev_b32_e32 v155, 16, v65
	v_and_b32_e32 v189, 0xffff0000, v65
	v_mul_f32_e32 v80, v80, v155
	v_mul_f32_e32 v81, v81, v189
	v_cvt_pk_bf16_f32 v64, v78, v79
	v_cvt_pk_bf16_f32 v65, v80, v81
	global_store_dwordx2 v93, v[64:65], s[68:69] offset:64
	s_waitcnt lgkmcnt(4)
	v_mfma_f32_16x16x32_bf16 v[78:81], v[200:203], v[44:47], 0
	v_mfma_f32_16x16x32_bf16 v[78:81], v[204:207], v[48:51], v[78:81]
	v_mfma_f32_16x16x32_bf16 v[78:81], v[208:211], v[52:55], v[78:81]
	v_mfma_f32_16x16x32_bf16 v[78:81], v[212:215], v[56:59], v[78:81]
	ds_read_b128 v[200:203], v87 offset:26112
	ds_read_b128 v[204:207], v87 offset:26176
	ds_read_b128 v[208:211], v87 offset:26240
	ds_read_b128 v[212:215], v87 offset:26304
	v_add_f32_e32 v94, v76, v94
	v_add_f32_e32 v95, v76, v95
	v_add_f32_e32 v96, v76, v96
	v_add_f32_e32 v97, v76, v97
	v_lshlrev_b32_e32 v155, 16, v66
	v_and_b32_e32 v189, 0xffff0000, v66
	v_mul_f32_e32 v94, v94, v155
	v_mul_f32_e32 v95, v95, v189
	v_lshlrev_b32_e32 v155, 16, v67
	v_and_b32_e32 v189, 0xffff0000, v67
	v_mul_f32_e32 v96, v96, v155
	v_mul_f32_e32 v97, v97, v189
	v_cvt_pk_bf16_f32 v66, v94, v95
	v_cvt_pk_bf16_f32 v67, v96, v97
	global_store_dwordx2 v93, v[66:67], s[68:69] offset:96
	s_waitcnt lgkmcnt(4)
	v_mfma_f32_16x16x32_bf16 v[94:97], v[216:219], v[44:47], 0
	v_mfma_f32_16x16x32_bf16 v[94:97], v[220:223], v[48:51], v[94:97]
	v_mfma_f32_16x16x32_bf16 v[94:97], v[224:227], v[52:55], v[94:97]
	v_mfma_f32_16x16x32_bf16 v[94:97], v[228:231], v[56:59], v[94:97]
	ds_read_b128 v[216:219], v87 offset:30464
	ds_read_b128 v[220:223], v87 offset:30528
	ds_read_b128 v[224:227], v87 offset:30592
	ds_read_b128 v[228:231], v87 offset:30656
	v_add_f32_e32 v78, v76, v78
	v_add_f32_e32 v79, v76, v79
	v_add_f32_e32 v80, v76, v80
	v_add_f32_e32 v81, v76, v81
	v_lshlrev_b32_e32 v155, 16, v68
	v_and_b32_e32 v189, 0xffff0000, v68
	v_mul_f32_e32 v78, v78, v155
	v_mul_f32_e32 v79, v79, v189
	v_lshlrev_b32_e32 v155, 16, v69
	v_and_b32_e32 v189, 0xffff0000, v69
	v_mul_f32_e32 v80, v80, v155
	v_mul_f32_e32 v81, v81, v189
	v_cvt_pk_bf16_f32 v68, v78, v79
	v_cvt_pk_bf16_f32 v69, v80, v81
	global_store_dwordx2 v93, v[68:69], s[68:69] offset:128
	s_waitcnt lgkmcnt(4)
	v_mfma_f32_16x16x32_bf16 v[78:81], v[200:203], v[44:47], 0
	v_mfma_f32_16x16x32_bf16 v[78:81], v[204:207], v[48:51], v[78:81]
	v_mfma_f32_16x16x32_bf16 v[78:81], v[208:211], v[52:55], v[78:81]
	v_mfma_f32_16x16x32_bf16 v[78:81], v[212:215], v[56:59], v[78:81]
	v_add_f32_e32 v94, v76, v94
	v_add_f32_e32 v95, v76, v95
	v_add_f32_e32 v96, v76, v96
	v_add_f32_e32 v97, v76, v97
	v_lshlrev_b32_e32 v155, 16, v70
	v_and_b32_e32 v189, 0xffff0000, v70
	v_mul_f32_e32 v94, v94, v155
	v_mul_f32_e32 v95, v95, v189
	v_lshlrev_b32_e32 v155, 16, v71
	v_and_b32_e32 v189, 0xffff0000, v71
	v_mul_f32_e32 v96, v96, v155
	v_mul_f32_e32 v97, v97, v189
	v_cvt_pk_bf16_f32 v70, v94, v95
	v_cvt_pk_bf16_f32 v71, v96, v97
	global_store_dwordx2 v93, v[70:71], s[68:69] offset:160
	s_waitcnt lgkmcnt(0)
	v_mfma_f32_16x16x32_bf16 v[94:97], v[216:219], v[44:47], 0
	v_mfma_f32_16x16x32_bf16 v[94:97], v[220:223], v[48:51], v[94:97]
	v_mfma_f32_16x16x32_bf16 v[94:97], v[224:227], v[52:55], v[94:97]
	v_mfma_f32_16x16x32_bf16 v[94:97], v[228:231], v[56:59], v[94:97]
	v_add_f32_e32 v78, v76, v78
	v_add_f32_e32 v79, v76, v79
	v_add_f32_e32 v80, v76, v80
	v_add_f32_e32 v81, v76, v81
	v_lshlrev_b32_e32 v155, 16, v72
	v_and_b32_e32 v189, 0xffff0000, v72
	v_mul_f32_e32 v78, v78, v155
	v_mul_f32_e32 v79, v79, v189
	v_lshlrev_b32_e32 v155, 16, v73
	v_and_b32_e32 v189, 0xffff0000, v73
	v_mul_f32_e32 v80, v80, v155
	v_mul_f32_e32 v81, v81, v189
	v_cvt_pk_bf16_f32 v72, v78, v79
	v_cvt_pk_bf16_f32 v73, v80, v81
	global_store_dwordx2 v93, v[72:73], s[68:69] offset:192
	s_nop 7
	v_add_f32_e32 v94, v76, v94
	v_add_f32_e32 v95, v76, v95
	v_add_f32_e32 v96, v76, v96
	v_add_f32_e32 v97, v76, v97
	v_lshlrev_b32_e32 v155, 16, v74
	v_and_b32_e32 v189, 0xffff0000, v74
	v_mul_f32_e32 v94, v94, v155
	v_mul_f32_e32 v95, v95, v189
	v_lshlrev_b32_e32 v155, 16, v75
	v_and_b32_e32 v189, 0xffff0000, v75
	v_mul_f32_e32 v96, v96, v155
	v_mul_f32_e32 v97, v97, v189
	v_cvt_pk_bf16_f32 v74, v94, v95
	v_cvt_pk_bf16_f32 v75, v96, v97
	global_store_dwordx2 v93, v[74:75], s[68:69] offset:224
	s_barrier
	s_mov_b32 s16, s70
	s_cmpk_lt_u32 s16, 0x600
	s_cbranch_scc0 .Lgm_done
	s_branch .Lgm_loop
.Lgm_done:
.LBB0_575:
	v_readlane_b32 s4, v244, 35
	v_readlane_b32 s5, v244, 36
	s_andn2_b64 vcc, exec, s[4:5]
	s_cbranch_vccnz .LBB0_582
	v_ashrrev_i32_e32 v118, 1, v83
	v_readlane_b32 s8, v245, 63
	s_add_u32 s4, s6, 0x3e00000
	s_addc_u32 s5, s7, 0
	v_add_u32_e32 v4, s8, v118
	v_ashrrev_i32_e32 v5, 31, v4
	v_readlane_b32 s8, v243, 41
	v_lshlrev_b64 v[4:5], 11, v[4:5]
	v_readlane_b32 s9, v243, 42
	v_lshlrev_b32_e32 v1, 5, v83
	v_lshl_add_u64 v[4:5], s[4:5], 0, v[4:5]
	s_mov_b32 s9, s37
	v_and_b32_e32 v36, 32, v1
	v_lshl_add_u64 v[4:5], v[4:5], 0, s[8:9]
	v_lshlrev_b32_e32 v6, 1, v36
	v_mov_b32_e32 v7, v3
	s_mov_b32 s10, s8
	v_lshl_add_u64 v[32:33], v[4:5], 0, v[6:7]
	s_movk_i32 s8, 0x90
	v_mul_u32_u24_e32 v4, 0x210, v36
	v_and_b32_e32 v5, -2, v83
	v_mul_lo_u32 v1, v118, s8
	v_add3_u32 v121, 0, v4, v5
	v_mul_u32_u24_e32 v4, 0x210, v84
	v_add3_u32 v119, 0, v1, v6
	v_add3_u32 v122, 0, v4, v2
	global_load_dwordx4 v[4:7], v[32:33], off offset:1072
	global_load_dwordx4 v[8:11], v[32:33], off offset:1056
	global_load_dwordx4 v[12:15], v[32:33], off offset:1040
	global_load_dwordx4 v[16:19], v[32:33], off offset:1024
	global_load_dwordx4 v[20:23], v[32:33], off offset:1536
	global_load_dwordx4 v[24:27], v[32:33], off offset:1552
	global_load_dwordx4 v[28:31], v[32:33], off offset:1568
	s_nop 0
	global_load_dwordx4 v[32:35], v[32:33], off offset:1584
	v_and_b32_e32 v39, 64, v197
	v_xor_b32_e32 v38, 16, v197
	v_add_u32_e32 v39, 64, v39
	v_cmp_lt_i32_e32 vcc, v38, v39
	v_writelane_b32 v243, s10, 41
	v_mov_b32_e32 v1, v3
	v_cndmask_b32_e32 v38, v197, v38, vcc
	v_lshlrev_b32_e32 v126, 2, v38
	v_xor_b32_e32 v38, 32, v197
	v_cmp_lt_i32_e32 vcc, v38, v39
	v_writelane_b32 v243, s11, 42
	s_movk_i32 s8, 0xffe0
	v_lshl_add_u64 v[0:1], s[6:7], 0, v[0:1]
	s_mov_b64 s[6:7], 0xc200000
	v_mul_u32_u24_e32 v37, 0x90, v84
	v_cndmask_b32_e32 v38, v197, v38, vcc
	v_and_or_b32 v120, v118, s8, v84
	v_lshl_add_u64 v[0:1], v[0:1], 0, s[6:7]
	v_add_u32_e32 v123, 0x2100, v122
	v_add_u32_e32 v124, 0x4200, v122
	v_add_u32_e32 v125, 0x6300, v122
	v_lshlrev_b32_e32 v127, 2, v38
	v_lshlrev_b32_e32 v112, 1, v36
	v_add_u32_e32 v128, v82, v37
	v_readlane_b32 s13, v243, 35
	v_readlane_b32 s10, v243, 31
	s_mov_b32 s11, s2
	s_branch .LBB0_578
